# no s_setprio in GEMM K-loops + FFN-up K-loop LDS-DMA in SGPR-base form (16 fewer 64-bit VALU adds per iteration) + barrier leader publishes generation before its own invalidate
# speedup vs baseline: 1.0090x; 1.0025x over previous
; #define PG8_STAGE(bufoff, gbase, voff) do { _Pragma("unroll") for (int _i = 0; _i < 2; ++_i) \
;         __builtin_amdgcn_global_load_lds((const GAS unsigned*)((const GAS char*)(gbase) + (voff)[_i]), (PG8_LAS unsigned*)(lds + (bufoff) + ldsw + _i * 8192), 16, 0, 0); } while (0)
; #define PG8_LDA(dst, b, h) do { _Pragma("unroll") for (int m = 0; m < 4; ++m) _Pragma("unroll") for (int k = 0; k < 2; ++k) dst[m][k] = *(const PG8_LAS bf16x8*)(lds + PG8_SA(b, h) + aoff + m * 2048 + k * 1024); } while (0)
; #define PG8_LDB(dst, b, h) do { _Pragma("unroll") for (int n = 0; n < 2; ++n) _Pragma("unroll") for (int k = 0; k < 2; ++k) dst[n][k] = *(const PG8_LAS bf16x8*)(lds + PG8_SB(b, h) + boff + n * 2048 + k * 1024); } while (0)
; #define PG8_MMA(ai, bj, At, Bt) do { __builtin_amdgcn_s_setprio(1); _Pragma("unroll") for (int m = 0; m < 4; ++m) _Pragma("unroll") for (int n = 0; n < 2; ++n) _Pragma("unroll") for (int k = 0; k < 2; ++k) \
;         acc[ai][bj][m][n] = __builtin_amdgcn_mfma_f32_16x16x32_bf16(Bt[n][k], At[m][k], acc[ai][bj][m][n], 0, 0, 0); __builtin_amdgcn_s_setprio(0); } while (0)
; #define PG8_WAIT_V(n) asm volatile("s_waitcnt vmcnt(" #n ")" ::: "memory")
; #define PG8_WAIT_L(n) asm volatile("s_waitcnt lgkmcnt(" #n ")" ::: "memory")
; #define PG8_BAR __builtin_amdgcn_s_barrier()
; #define PG8_SCHED __builtin_amdgcn_sched_barrier(0)
; #define PG8_LDA(dst, b, h) do { _Pragma("unroll") for (int m = 0; m < 4; ++m) _Pragma("unroll") for (int k = 0; k < 2; ++k) dst[m][k] = *(const PG8_LAS bf16x8*)(lds + PG8_SA(b, h) + aoff + m * 2048 + k * 1024); } while (0)
; template <class Epi, class Sched, bool ALIGN_EPI = false, bool SP2 = false>
; __device__ __forceinline__ void gemm_phase(PG8_LAS unsigned char* lds, PG8_LAS unsigned char* pf, const Gemm g, const Sched& S, const Epi& E, int wv) {
;     ...
;             PG8_LDB(B0, 0, 0); PG8_LDB(B1, 0, 1); PG8_SCHED; PG8_LDA(At, 0, 0); PG8_STAGE(PG8_SA(1, 1), a1 + (Sched::SPLIT ? hsA : (long)hstepA), voffA);
;             PG8_WAIT_V(8); PG8_WAIT_L(0); PG8_BAR; PG8_MMA(0, 0, At, B0); PG8_MMA(0, 1, At, B1); PG8_BAR; PG8_SCHED;
;             PG8_LDA(At, 0, 1); PG8_STAGE(PG8_SB(0, 0), b2, voffB); PG8_STAGE(PG8_SB(0, 1), b2 + hstepB, voffB); PG8_STAGE(PG8_SA(0, 0), a2, voffA);
;             PG8_WAIT_V(8); PG8_WAIT_L(0); PG8_BAR; PG8_MMA(1, 0, At, B0); PG8_MMA(1, 1, At, B1); PG8_BAR; PG8_SCHED;
.LBB0_1414:
	s_add_u32 s25, s36, 0xfff80080
	s_addc_u32 s28, s37, -1
	s_add_i32 s42, 0, 0x10000
	s_cmp_eq_u32 s24, 28
	s_cselect_b32 s29, s13, s28
	s_cselect_b32 s28, s12, s25
	s_cselect_b32 s41, s9, s23
	s_cselect_b32 s40, s11, s22
	s_add_i32 s25, 0, 0x14000
	v_add_u32_e32 v132, s42, v159
	v_add_u32_e32 v160, s25, v159
	ds_read_b128 v[120:123], v132
	ds_read_b128 v[124:127], v132 offset:1024
	ds_read_b128 v[128:131], v132 offset:2048
	ds_read_b128 v[132:135], v132 offset:3072
	ds_read_b128 v[164:167], v160
	ds_read_b128 v[168:171], v160 offset:1024
	ds_read_b128 v[172:175], v160 offset:2048
	ds_read_b128 v[176:179], v160 offset:3072
	s_add_i32 m0, s1, 0xc000
	ds_read_b128 v[180:183], v162
	ds_read_b128 v[184:187], v162 offset:1024
	ds_read_b128 v[188:191], v162 offset:2048
	ds_read_b128 v[192:195], v162 offset:3072
	ds_read_b128 v[196:199], v162 offset:4096
	ds_read_b128 v[200:203], v162 offset:5120
	ds_read_b128 v[204:207], v162 offset:6144
	ds_read_b128 v[214:217], v162 offset:7168
	global_load_lds_dwordx4 v154, s[36:37]
	s_add_i32 m0, s1, 0xe000
	s_nop 0
	global_load_lds_dwordx4 v152, s[36:37]
	s_waitcnt vmcnt(8)
	s_waitcnt lgkmcnt(0)
	s_barrier
	s_waitcnt lgkmcnt(0)
	v_mfma_f32_16x16x32_bf16 v[140:143], v[120:123], v[180:183], v[140:143]
	v_mfma_f32_16x16x32_bf16 v[136:139], v[128:131], v[180:183], v[136:139]
	v_mfma_f32_16x16x32_bf16 v[108:111], v[120:123], v[188:191], v[108:111]
	v_mfma_f32_16x16x32_bf16 v[104:107], v[128:131], v[188:191], v[104:107]
	v_mfma_f32_16x16x32_bf16 v[92:95], v[120:123], v[196:199], v[92:95]
	v_mfma_f32_16x16x32_bf16 v[88:91], v[128:131], v[196:199], v[88:91]
	v_mfma_f32_16x16x32_bf16 v[76:79], v[120:123], v[204:207], v[76:79]
	v_mfma_f32_16x16x32_bf16 v[72:75], v[128:131], v[204:207], v[72:75]
	v_mfma_f32_16x16x32_bf16 v[140:143], v[124:127], v[184:187], v[140:143]
	v_mfma_f32_16x16x32_bf16 v[136:139], v[132:135], v[184:187], v[136:139]
	v_mfma_f32_16x16x32_bf16 v[108:111], v[124:127], v[192:195], v[108:111]
	v_mfma_f32_16x16x32_bf16 v[104:107], v[132:135], v[192:195], v[104:107]
	v_mfma_f32_16x16x32_bf16 v[92:95], v[124:127], v[200:203], v[92:95]
	v_mfma_f32_16x16x32_bf16 v[88:91], v[132:135], v[200:203], v[88:91]
	v_mfma_f32_16x16x32_bf16 v[76:79], v[124:127], v[214:217], v[76:79]
	v_mfma_f32_16x16x32_bf16 v[72:75], v[132:135], v[214:217], v[72:75]
	v_mfma_f32_16x16x32_bf16 v[116:119], v[164:167], v[180:183], v[116:119]
	v_mfma_f32_16x16x32_bf16 v[112:115], v[172:175], v[180:183], v[112:115]
	v_mfma_f32_16x16x32_bf16 v[100:103], v[164:167], v[188:191], v[100:103]
	v_mfma_f32_16x16x32_bf16 v[96:99], v[172:175], v[188:191], v[96:99]
	v_mfma_f32_16x16x32_bf16 v[84:87], v[164:167], v[196:199], v[84:87]
	v_mfma_f32_16x16x32_bf16 v[80:83], v[172:175], v[196:199], v[80:83]
	v_mfma_f32_16x16x32_bf16 v[68:71], v[164:167], v[204:207], v[68:71]
	v_mfma_f32_16x16x32_bf16 v[64:67], v[172:175], v[204:207], v[64:67]
	v_mfma_f32_16x16x32_bf16 v[116:119], v[168:171], v[184:187], v[116:119]
	v_mfma_f32_16x16x32_bf16 v[112:115], v[176:179], v[184:187], v[112:115]
	v_mfma_f32_16x16x32_bf16 v[100:103], v[168:171], v[192:195], v[100:103]
	v_mfma_f32_16x16x32_bf16 v[96:99], v[176:179], v[192:195], v[96:99]
	v_mfma_f32_16x16x32_bf16 v[84:87], v[168:171], v[200:203], v[84:87]
	v_mfma_f32_16x16x32_bf16 v[80:83], v[176:179], v[200:203], v[80:83]
	v_mfma_f32_16x16x32_bf16 v[68:71], v[168:171], v[214:217], v[68:71]
	v_mfma_f32_16x16x32_bf16 v[64:67], v[176:179], v[214:217], v[64:67]
	s_barrier
	s_add_i32 s42, s42, s27
	s_mov_b32 m0, s42
	ds_read_b128 v[180:183], v162 offset:16384
	ds_read_b128 v[184:187], v162 offset:17408
	ds_read_b128 v[188:191], v162 offset:18432
	ds_read_b128 v[192:195], v162 offset:19456
	ds_read_b128 v[196:199], v162 offset:20480
	ds_read_b128 v[200:203], v162 offset:21504
	ds_read_b128 v[204:207], v162 offset:22528
	ds_read_b128 v[214:217], v162 offset:23552
	global_load_lds_dwordx4 v146, s[40:41]
	s_add_i32 m0, s42, 0x2000
	s_add_u32 s42, s40, 0x80000
	s_addc_u32 s43, s41, 0
	s_add_i32 s25, s25, s27
	global_load_lds_dwordx4 v150, s[40:41]
	s_mov_b32 m0, s25
	s_nop 0
	global_load_lds_dwordx4 v146, s[42:43]
	s_add_i32 m0, s25, 0x2000
	s_nop 0
	global_load_lds_dwordx4 v150, s[42:43]
	s_mov_b32 m0, s1
	s_nop 0
	global_load_lds_dwordx4 v144, s[28:29]
	s_mov_b32 m0, s39
	s_nop 0
	global_load_lds_dwordx4 v148, s[28:29]
	s_waitcnt vmcnt(8)
	s_waitcnt lgkmcnt(0)
	s_barrier
	s_waitcnt lgkmcnt(0)
	v_mfma_f32_16x16x32_bf16 v[60:63], v[120:123], v[180:183], v[60:63]
	v_mfma_f32_16x16x32_bf16 v[56:59], v[128:131], v[180:183], v[56:59]
	v_mfma_f32_16x16x32_bf16 v[44:47], v[120:123], v[188:191], v[44:47]
	v_mfma_f32_16x16x32_bf16 v[40:43], v[128:131], v[188:191], v[40:43]
	v_mfma_f32_16x16x32_bf16 v[28:31], v[120:123], v[196:199], v[28:31]
	v_mfma_f32_16x16x32_bf16 v[24:27], v[128:131], v[196:199], v[24:27]
	v_mfma_f32_16x16x32_bf16 v[12:15], v[120:123], v[204:207], v[12:15]
	v_mfma_f32_16x16x32_bf16 v[8:11], v[128:131], v[204:207], v[8:11]
	v_mfma_f32_16x16x32_bf16 v[60:63], v[124:127], v[184:187], v[60:63]
	v_mfma_f32_16x16x32_bf16 v[56:59], v[132:135], v[184:187], v[56:59]
	v_mfma_f32_16x16x32_bf16 v[44:47], v[124:127], v[192:195], v[44:47]
	v_mfma_f32_16x16x32_bf16 v[40:43], v[132:135], v[192:195], v[40:43]
	v_mfma_f32_16x16x32_bf16 v[28:31], v[124:127], v[200:203], v[28:31]
	v_mfma_f32_16x16x32_bf16 v[24:27], v[132:135], v[200:203], v[24:27]
	v_mfma_f32_16x16x32_bf16 v[12:15], v[124:127], v[214:217], v[12:15]
	v_mfma_f32_16x16x32_bf16 v[8:11], v[132:135], v[214:217], v[8:11]
	v_mfma_f32_16x16x32_bf16 v[52:55], v[164:167], v[180:183], v[52:55]
	v_mfma_f32_16x16x32_bf16 v[48:51], v[172:175], v[180:183], v[48:51]
	v_mfma_f32_16x16x32_bf16 v[36:39], v[164:167], v[188:191], v[36:39]
	v_mfma_f32_16x16x32_bf16 v[32:35], v[172:175], v[188:191], v[32:35]
	v_mfma_f32_16x16x32_bf16 v[20:23], v[164:167], v[196:199], v[20:23]
	v_mfma_f32_16x16x32_bf16 v[16:19], v[172:175], v[196:199], v[16:19]
	v_mfma_f32_16x16x32_bf16 v[4:7], v[164:167], v[204:207], v[4:7]
	v_mfma_f32_16x16x32_bf16 v[0:3], v[172:175], v[204:207], v[0:3]
	v_mfma_f32_16x16x32_bf16 v[52:55], v[168:171], v[184:187], v[52:55]
	v_mfma_f32_16x16x32_bf16 v[48:51], v[176:179], v[184:187], v[48:51]
	v_mfma_f32_16x16x32_bf16 v[36:39], v[168:171], v[192:195], v[36:39]
	v_mfma_f32_16x16x32_bf16 v[32:35], v[176:179], v[192:195], v[32:35]
	v_mfma_f32_16x16x32_bf16 v[20:23], v[168:171], v[200:203], v[20:23]
	v_mfma_f32_16x16x32_bf16 v[16:19], v[176:179], v[200:203], v[16:19]
	v_mfma_f32_16x16x32_bf16 v[4:7], v[168:171], v[214:217], v[4:7]
	v_mfma_f32_16x16x32_bf16 v[0:3], v[176:179], v[214:217], v[0:3]
	s_barrier
; #define GAS __attribute__((address_space(1)))
; #define PG8_STAGE(bufoff, gbase, voff) do { _Pragma("unroll") for (int _i = 0; _i < 2; ++_i) \
;         __builtin_amdgcn_global_load_lds((const GAS unsigned*)((const GAS char*)(gbase) + (voff)[_i]), (PG8_LAS unsigned*)(lds + (bufoff) + ldsw + _i * 8192), 16, 0, 0); } while (0)
; #define PG8_LDA(dst, b, h) do { _Pragma("unroll") for (int m = 0; m < 4; ++m) _Pragma("unroll") for (int k = 0; k < 2; ++k) dst[m][k] = *(const PG8_LAS bf16x8*)(lds + PG8_SA(b, h) + aoff + m * 2048 + k * 1024); } while (0)
; #define PG8_LDB(dst, b, h) do { _Pragma("unroll") for (int n = 0; n < 2; ++n) _Pragma("unroll") for (int k = 0; k < 2; ++k) dst[n][k] = *(const PG8_LAS bf16x8*)(lds + PG8_SB(b, h) + boff + n * 2048 + k * 1024); } while (0)
; #define PG8_MMA(ai, bj, At, Bt) do { __builtin_amdgcn_s_setprio(1); _Pragma("unroll") for (int m = 0; m < 4; ++m) _Pragma("unroll") for (int n = 0; n < 2; ++n) _Pragma("unroll") for (int k = 0; k < 2; ++k) \
;         acc[ai][bj][m][n] = __builtin_amdgcn_mfma_f32_16x16x32_bf16(Bt[n][k], At[m][k], acc[ai][bj][m][n], 0, 0, 0); __builtin_amdgcn_s_setprio(0); } while (0)
; #define PG8_WAIT_V(n) asm volatile("s_waitcnt vmcnt(" #n ")" ::: "memory")
; template <class Epi, class Sched, bool ALIGN_EPI = false, bool SP2 = false>
; __device__ __forceinline__ void gemm_phase(PG8_LAS unsigned char* lds, PG8_LAS unsigned char* pf, const Gemm g, const Sched& S, const Epi& E, int wv) {
;     ...
;         for (int t = 0; t < ntu; t += 2) {
;             const bool last = (t == ntu - 2);
;             const GAS char* a1 = cA + (size_t)(t + 1) * kstep;
;             const GAS char* a2 = last ? nA : cA + (size_t)(t + 2) * kstep; const GAS char* b2 = last ? nB : cB + (size_t)(t + 2) * kstep;
;     ...
;             PG8_LDB(B0, 1, 0); PG8_LDB(B1, 1, 1); PG8_SCHED; PG8_LDA(At, 1, 0); PG8_STAGE(PG8_SA(0, 1), a2 + (Sched::SPLIT ? ((last && has_next) ? (nxt.kh > 0 ? -(long)hstepA : (long)hstepA) : hsA) : (long)hstepA), voffA);
;             PG8_WAIT_V(8); PG8_WAIT_L(0); PG8_BAR; PG8_MMA(0, 0, At, B0); PG8_MMA(0, 1, At, B1); PG8_BAR; PG8_SCHED;
;             PG8_LDA(At, 1, 1); PG8_STAGE(PG8_SB(1, 0), b3, voffB); PG8_STAGE(PG8_SB(1, 1), b3 + hstepB, voffB); PG8_STAGE(PG8_SA(1, 0), a3, voffA);
;             PG8_WAIT_V(8); PG8_WAIT_L(0); PG8_BAR; PG8_MMA(1, 0, At, B0); PG8_MMA(1, 1, At, B1); PG8_BAR; PG8_SCHED;
	s_add_i32 s25, 0, 0x18000
	s_add_i32 s42, 0, 0x1c000
	v_add_u32_e32 v132, s25, v159
	v_add_u32_e32 v160, s42, v159
	ds_read_b128 v[120:123], v132
	ds_read_b128 v[124:127], v132 offset:1024
	ds_read_b128 v[128:131], v132 offset:2048
	ds_read_b128 v[132:135], v132 offset:3072
	ds_read_b128 v[164:167], v160
	ds_read_b128 v[168:171], v160 offset:1024
	ds_read_b128 v[172:175], v160 offset:2048
	ds_read_b128 v[176:179], v160 offset:3072
	s_add_u32 s28, s28, 0x80000
	s_addc_u32 s29, s29, 0
	s_mov_b32 m0, s44
	ds_read_b128 v[180:183], v162 offset:32768
	ds_read_b128 v[184:187], v162 offset:33792
	ds_read_b128 v[188:191], v162 offset:34816
	ds_read_b128 v[192:195], v162 offset:35840
	ds_read_b128 v[196:199], v162 offset:36864
	ds_read_b128 v[200:203], v162 offset:37888
	ds_read_b128 v[204:207], v162 offset:38912
	ds_read_b128 v[214:217], v162 offset:39936
	global_load_lds_dwordx4 v144, s[28:29]
	s_mov_b32 m0, s45
	s_nop 0
	global_load_lds_dwordx4 v148, s[28:29]
	s_waitcnt vmcnt(8)
	s_waitcnt lgkmcnt(0)
	s_barrier
	s_waitcnt lgkmcnt(0)
	v_mfma_f32_16x16x32_bf16 v[140:143], v[120:123], v[180:183], v[140:143]
	v_mfma_f32_16x16x32_bf16 v[136:139], v[128:131], v[180:183], v[136:139]
	v_mfma_f32_16x16x32_bf16 v[108:111], v[120:123], v[188:191], v[108:111]
	v_mfma_f32_16x16x32_bf16 v[104:107], v[128:131], v[188:191], v[104:107]
	v_mfma_f32_16x16x32_bf16 v[92:95], v[120:123], v[196:199], v[92:95]
	v_mfma_f32_16x16x32_bf16 v[88:91], v[128:131], v[196:199], v[88:91]
	v_mfma_f32_16x16x32_bf16 v[76:79], v[120:123], v[204:207], v[76:79]
	v_mfma_f32_16x16x32_bf16 v[72:75], v[128:131], v[204:207], v[72:75]
	v_mfma_f32_16x16x32_bf16 v[140:143], v[124:127], v[184:187], v[140:143]
	v_mfma_f32_16x16x32_bf16 v[136:139], v[132:135], v[184:187], v[136:139]
	v_mfma_f32_16x16x32_bf16 v[108:111], v[124:127], v[192:195], v[108:111]
	v_mfma_f32_16x16x32_bf16 v[104:107], v[132:135], v[192:195], v[104:107]
	v_mfma_f32_16x16x32_bf16 v[92:95], v[124:127], v[200:203], v[92:95]
	v_mfma_f32_16x16x32_bf16 v[88:91], v[132:135], v[200:203], v[88:91]
	v_mfma_f32_16x16x32_bf16 v[76:79], v[124:127], v[214:217], v[76:79]
	v_mfma_f32_16x16x32_bf16 v[72:75], v[132:135], v[214:217], v[72:75]
	v_mfma_f32_16x16x32_bf16 v[116:119], v[164:167], v[180:183], v[116:119]
	v_mfma_f32_16x16x32_bf16 v[112:115], v[172:175], v[180:183], v[112:115]
	v_mfma_f32_16x16x32_bf16 v[100:103], v[164:167], v[188:191], v[100:103]
	v_mfma_f32_16x16x32_bf16 v[96:99], v[172:175], v[188:191], v[96:99]
	v_mfma_f32_16x16x32_bf16 v[84:87], v[164:167], v[196:199], v[84:87]
	v_mfma_f32_16x16x32_bf16 v[80:83], v[172:175], v[196:199], v[80:83]
	v_mfma_f32_16x16x32_bf16 v[68:71], v[164:167], v[204:207], v[68:71]
	v_mfma_f32_16x16x32_bf16 v[64:67], v[172:175], v[204:207], v[64:67]
	v_mfma_f32_16x16x32_bf16 v[116:119], v[168:171], v[184:187], v[116:119]
	v_mfma_f32_16x16x32_bf16 v[112:115], v[176:179], v[184:187], v[112:115]
	v_mfma_f32_16x16x32_bf16 v[100:103], v[168:171], v[192:195], v[100:103]
	v_mfma_f32_16x16x32_bf16 v[96:99], v[176:179], v[192:195], v[96:99]
	v_mfma_f32_16x16x32_bf16 v[84:87], v[168:171], v[200:203], v[84:87]
	v_mfma_f32_16x16x32_bf16 v[80:83], v[176:179], v[200:203], v[80:83]
	v_mfma_f32_16x16x32_bf16 v[68:71], v[168:171], v[214:217], v[68:71]
	v_mfma_f32_16x16x32_bf16 v[64:67], v[176:179], v[214:217], v[64:67]
	s_barrier
	s_add_i32 s25, s25, s27
	s_add_u32 s98, s28, 0xfff80080
	s_addc_u32 s99, s29, -1
	s_mov_b32 m0, s20
	ds_read_b128 v[180:183], v162 offset:49152
	ds_read_b128 v[184:187], v162 offset:50176
	ds_read_b128 v[188:191], v162 offset:51200
	ds_read_b128 v[192:195], v162 offset:52224
	ds_read_b128 v[196:199], v162 offset:53248
	ds_read_b128 v[200:203], v162 offset:54272
	ds_read_b128 v[204:207], v162 offset:55296
	ds_read_b128 v[214:217], v162 offset:56320
	global_load_lds_dwordx4 v144, s[98:99]
	s_mov_b32 m0, s21
	s_nop 0
	global_load_lds_dwordx4 v148, s[98:99]
	s_add_u32 s98, s40, 0x80
	s_addc_u32 s99, s41, 0
	s_mov_b32 m0, s25
	s_add_u32 s28, s40, 0x80080
	s_addc_u32 s29, s41, 0
	global_load_lds_dwordx4 v146, s[98:99]
	s_add_i32 m0, s25, 0x2000
	s_add_i32 s25, s42, s27
	global_load_lds_dwordx4 v150, s[98:99]
	s_mov_b32 m0, s25
	s_nop 0
	global_load_lds_dwordx4 v146, s[28:29]
	s_add_i32 m0, s25, 0x2000
	s_nop 0
	global_load_lds_dwordx4 v150, s[28:29]
	s_waitcnt vmcnt(8)
	s_waitcnt lgkmcnt(0)
	s_barrier
	s_waitcnt lgkmcnt(0)
	v_mfma_f32_16x16x32_bf16 v[60:63], v[120:123], v[180:183], v[60:63]
	v_mfma_f32_16x16x32_bf16 v[56:59], v[128:131], v[180:183], v[56:59]
	v_mfma_f32_16x16x32_bf16 v[44:47], v[120:123], v[188:191], v[44:47]
	v_mfma_f32_16x16x32_bf16 v[40:43], v[128:131], v[188:191], v[40:43]
	v_mfma_f32_16x16x32_bf16 v[28:31], v[120:123], v[196:199], v[28:31]
	v_mfma_f32_16x16x32_bf16 v[24:27], v[128:131], v[196:199], v[24:27]
	v_mfma_f32_16x16x32_bf16 v[12:15], v[120:123], v[204:207], v[12:15]
	v_mfma_f32_16x16x32_bf16 v[8:11], v[128:131], v[204:207], v[8:11]
	v_mfma_f32_16x16x32_bf16 v[60:63], v[124:127], v[184:187], v[60:63]
	v_mfma_f32_16x16x32_bf16 v[56:59], v[132:135], v[184:187], v[56:59]
	v_mfma_f32_16x16x32_bf16 v[44:47], v[124:127], v[192:195], v[44:47]
	v_mfma_f32_16x16x32_bf16 v[40:43], v[132:135], v[192:195], v[40:43]
	v_mfma_f32_16x16x32_bf16 v[28:31], v[124:127], v[200:203], v[28:31]
	v_mfma_f32_16x16x32_bf16 v[24:27], v[132:135], v[200:203], v[24:27]
	v_mfma_f32_16x16x32_bf16 v[12:15], v[124:127], v[214:217], v[12:15]
	v_mfma_f32_16x16x32_bf16 v[8:11], v[132:135], v[214:217], v[8:11]
	v_mfma_f32_16x16x32_bf16 v[52:55], v[164:167], v[180:183], v[52:55]
	v_mfma_f32_16x16x32_bf16 v[48:51], v[172:175], v[180:183], v[48:51]
	v_mfma_f32_16x16x32_bf16 v[36:39], v[164:167], v[188:191], v[36:39]
	v_mfma_f32_16x16x32_bf16 v[32:35], v[172:175], v[188:191], v[32:35]
	v_mfma_f32_16x16x32_bf16 v[20:23], v[164:167], v[196:199], v[20:23]
	v_mfma_f32_16x16x32_bf16 v[16:19], v[172:175], v[196:199], v[16:19]
	v_mfma_f32_16x16x32_bf16 v[4:7], v[164:167], v[204:207], v[4:7]
	v_mfma_f32_16x16x32_bf16 v[0:3], v[172:175], v[204:207], v[0:3]
	v_mfma_f32_16x16x32_bf16 v[52:55], v[168:171], v[184:187], v[52:55]
	v_mfma_f32_16x16x32_bf16 v[48:51], v[176:179], v[184:187], v[48:51]
	v_mfma_f32_16x16x32_bf16 v[36:39], v[168:171], v[192:195], v[36:39]
	v_mfma_f32_16x16x32_bf16 v[32:35], v[176:179], v[192:195], v[32:35]
	v_mfma_f32_16x16x32_bf16 v[20:23], v[168:171], v[200:203], v[20:23]
	v_mfma_f32_16x16x32_bf16 v[16:19], v[176:179], v[200:203], v[16:19]
	v_mfma_f32_16x16x32_bf16 v[4:7], v[168:171], v[214:217], v[4:7]
	v_mfma_f32_16x16x32_bf16 v[0:3], v[176:179], v[214:217], v[0:3]
	s_barrier
	s_add_i32 s24, s24, 2
	s_add_u32 s22, s22, 0x100
	s_addc_u32 s23, s23, 0
	s_add_u32 s36, s36, 0x100
	s_addc_u32 s37, s37, 0
	s_cmp_gt_u32 s24, 29
	s_cbranch_scc0 .LBB0_1414
	s_and_b64 vcc, exec, s[6:7]
	s_cbranch_vccz .LBB0_1417
	s_barrier
